# LN row-stat exchange: stats stored/loaded as wider sc1 accesses; dropped the L2 writeback/invalidate around the exchange (all exchanged data moves through device-scope sc1 stores/loads)
# speedup vs baseline: 1.0088x; 1.0088x over previous
; DI void ln_exchange(const AccT& acc, LAS float* red, float* stats, unsigned* cnt, int pm, int pn, int tid, int wr, int wc, int fr, int fq) {
;     ...
;   if (tid < 256) { float a = 0.f, b = 0.f;
; #pragma unroll
;     for (int w = 0; w < 4; ++w) { a += red[(tid * 4 + w) * 2]; b += red[(tid * 4 + w) * 2 + 1]; }
;     float* sp = stats + ((size_t)(pm * 256 + tid) * 8 + pn) * 2;
;     __hip_atomic_store(sp, a, __ATOMIC_RELAXED, __HIP_MEMORY_SCOPE_AGENT); __hip_atomic_store(sp + 1, b, __ATOMIC_RELAXED, __HIP_MEMORY_SCOPE_AGENT); }
;   asm volatile("s_waitcnt vmcnt(0)" ::: "memory");
;   __syncthreads();
;   if (tid == 0) {
;     __builtin_amdgcn_fence(__ATOMIC_RELEASE, "agent");
;     asm volatile("s_waitcnt vmcnt(0)" ::: "memory");
;     __hip_atomic_fetch_add(cnt + pm, 1u, __ATOMIC_RELAXED, __HIP_MEMORY_SCOPE_AGENT);
.LBB0_1801:
	s_or_b64 exec, exec, s[2:3]
	s_movk_i32 s2, 0x100
	v_add_u32_e32 v182, s22, v166
	v_cmp_gt_i32_e64 s[2:3], s2, v166
	v_lshl_add_u32 v209, v166, 5, 0
	v_ashrrev_i32_e32 v183, 31, v182
	s_waitcnt lgkmcnt(0)
	s_barrier
	s_and_saveexec_b64 s[4:5], s[2:3]
	s_cbranch_execz .LBB0_1803
	ds_read_b128 v[130:133], v209
	ds_read_b128 v[134:137], v209 offset:16
	v_readlane_b32 s14, v251, 28
	v_readlane_b32 s15, v251, 29
	s_ashr_i32 s11, s10, 31
	s_waitcnt lgkmcnt(1)
	v_add_f32_e32 v130, 0, v130
	v_add_f32_e32 v131, 0, v131
	v_add_f32_e32 v130, v130, v132
	v_add_f32_e32 v131, v131, v133
	s_waitcnt lgkmcnt(0)
	v_add_f32_e32 v130, v130, v134
	v_add_f32_e32 v131, v131, v135
	v_add_f32_e32 v132, v130, v136
	v_add_f32_e32 v133, v131, v137
	v_lshlrev_b64 v[130:131], 6, v[182:183]
	v_lshl_add_u64 v[130:131], s[14:15], 0, v[130:131]
	v_lshl_add_u64 v[130:131], s[10:11], 3, v[130:131]
	global_store_dwordx2 v[130:131], v[132:133], off sc1
.LBB0_1803:
	s_or_b64 exec, exec, s[4:5]
	v_readlane_b32 s4, v252, 29
	s_lshl_b32 s72, s4, 7
	s_lshl_b64 s[4:5], s[72:73], 2
	v_readlane_b32 s9, v251, 30
	s_waitcnt vmcnt(0)
	s_add_u32 s24, s9, s4
	v_readlane_b32 s4, v251, 31
	s_addc_u32 s25, s4, s5
	v_cmp_eq_u32_e64 s[4:5], 0, v166
	s_barrier
	s_and_saveexec_b64 s[14:15], s[4:5]
	s_cbranch_execz .LBB0_1820
	s_mov_b64 s[18:19], exec
	s_ashr_i32 s9, s8, 31
	s_waitcnt vmcnt(0)
	s_waitcnt vmcnt(0)
	s_lshl_b64 s[16:17], s[8:9], 2
	v_mbcnt_lo_u32_b32 v130, s18, 0
	s_add_u32 s16, s24, s16
	v_mbcnt_hi_u32_b32 v130, s19, v130
	s_addc_u32 s17, s25, s17
	v_cmp_eq_u32_e32 vcc, 0, v130
	s_and_saveexec_b64 s[20:21], vcc
	s_cbranch_execz .LBB0_1806
	s_bcnt1_i32_b64 s9, s[18:19]
	v_mov_b32_e32 v130, s9
	global_atomic_add v1, v130, s[16:17]

; DI void ln_exchange(const AccT& acc, LAS float* red, float* stats, unsigned* cnt, int pm, int pn, int tid, int wr, int wc, int fr, int fq) {
;     ...
;     while (__hip_atomic_load(cnt + pm, __ATOMIC_RELAXED, __HIP_MEMORY_SCOPE_AGENT) < 8u) { __builtin_amdgcn_s_sleep(1); if (++sp_ > (1u << 24)) break; }
;     __builtin_amdgcn_fence(__ATOMIC_ACQUIRE, "agent");
;     asm volatile("s_waitcnt vmcnt(0)" ::: "memory");
;   }
;   __syncthreads();
;   if (tid < 256) { float a = 0.f, b = 0.f; const float* sp = stats + (size_t)(pm * 256 + tid) * 16;
; #pragma unroll
;     for (int w = 0; w < 8; ++w) { a += __hip_atomic_load(sp + 2 * w, __ATOMIC_RELAXED, __HIP_MEMORY_SCOPE_AGENT); b += __hip_atomic_load(sp + 2 * w + 1, __ATOMIC_RELAXED, __HIP_MEMORY_SCOPE_AGENT); }
;     const float mean = a * (1.f / DM), var = fmaxf(b * (1.f / DM) - mean * mean, 0.f);
;     red[2048 + tid * 2] = mean; red[2048 + tid * 2 + 1] = rsqrtf(var + 1e-5f); }
.LBB0_1809:
	global_load_dword v130, v1, s[16:17] sc1
	s_mov_b64 s[18:19], -1
	s_waitcnt vmcnt(0)
	v_cmp_lt_u32_e32 vcc, 7, v130
	s_cbranch_vccnz .LBB0_1808
	s_cmp_lg_u32 s9, 0
	s_sleep 1
	s_cbranch_scc0 .LBB0_1807
	global_load_dword v130, v1, s[16:17] sc1
	s_waitcnt vmcnt(0)
	v_cmp_gt_u32_e32 vcc, 8, v130
	s_cbranch_vccz .LBB0_1808
	s_sleep 1
	global_load_dword v130, v1, s[16:17] sc1
	s_waitcnt vmcnt(0)
	v_cmp_gt_u32_e32 vcc, 8, v130
	s_cbranch_vccz .LBB0_1808
	s_sleep 1
	global_load_dword v130, v1, s[16:17] sc1
	s_waitcnt vmcnt(0)
	v_cmp_gt_u32_e32 vcc, 8, v130
	s_cbranch_vccz .LBB0_1808
	s_sleep 1
	global_load_dword v130, v1, s[16:17] sc1
	s_waitcnt vmcnt(0)
	v_cmp_gt_u32_e32 vcc, 8, v130
	s_cbranch_vccz .LBB0_1808
	s_sleep 1
	global_load_dword v130, v1, s[16:17] sc1
	s_waitcnt vmcnt(0)
	v_cmp_gt_u32_e32 vcc, 8, v130
	s_cbranch_vccz .LBB0_1808
	s_sleep 1
	global_load_dword v130, v1, s[16:17] sc1
	s_waitcnt vmcnt(0)
	v_cmp_gt_u32_e32 vcc, 8, v130
	s_cbranch_vccz .LBB0_1808
	s_sleep 1
	global_load_dword v130, v1, s[16:17] sc1
	s_waitcnt vmcnt(0)
	v_cmp_gt_u32_e32 vcc, 8, v130
	s_cbranch_vccz .LBB0_1808
	s_sleep 1
	s_add_i32 s9, s9, -8
	s_mov_b64 s[18:19], 0
	s_branch .LBB0_1808
.LBB0_1819:
	s_waitcnt vmcnt(0)
.LBB0_1820:
	s_or_b64 exec, exec, s[14:15]
	v_lshl_add_u32 v206, v166, 3, 0
	s_barrier
	s_and_saveexec_b64 s[14:15], s[2:3]
	s_cbranch_execz .LBB0_1822
	v_readlane_b32 s16, v251, 28
	v_lshlrev_b64 v[130:131], 6, v[182:183]
	v_readlane_b32 s17, v251, 29
	s_nop 1
	v_lshl_add_u64 v[130:131], s[16:17], 0, v[130:131]
	global_load_dwordx4 v[132:135], v[130:131], off sc1
	global_load_dwordx4 v[136:139], v[130:131], off offset:16 sc1
	global_load_dwordx4 v[140:143], v[130:131], off offset:32 sc1
	global_load_dwordx4 v[144:147], v[130:131], off offset:48 sc1
	s_mov_b32 s16, 0x3a000000
	s_waitcnt vmcnt(3)
	v_pk_add_f32 v[130:131], v[132:133], 0 op_sel:[1,0] op_sel_hi:[0,0]
	v_pk_add_f32 v[130:131], v[130:131], v[134:135] op_sel:[0,1] op_sel_hi:[1,0]
	s_waitcnt vmcnt(2)
	v_pk_add_f32 v[130:131], v[130:131], v[136:137] op_sel:[0,1] op_sel_hi:[1,0]
	v_pk_add_f32 v[130:131], v[130:131], v[138:139] op_sel:[0,1] op_sel_hi:[1,0]
	s_waitcnt vmcnt(1)
	v_pk_add_f32 v[130:131], v[130:131], v[140:141] op_sel:[0,1] op_sel_hi:[1,0]
	v_pk_add_f32 v[130:131], v[130:131], v[142:143] op_sel:[0,1] op_sel_hi:[1,0]
	s_waitcnt vmcnt(0)
	v_pk_add_f32 v[130:131], v[130:131], v[144:145] op_sel:[0,1] op_sel_hi:[1,0]
	v_pk_add_f32 v[130:131], v[130:131], v[146:147] op_sel:[0,1] op_sel_hi:[1,0]
	s_nop 0
	v_pk_mul_f32 v[130:131], v[130:131], s[16:17] op_sel_hi:[1,0]
	s_nop 0
	v_fma_f32 v130, -v131, v131, v130
	v_max_f32_e32 v130, 0, v130
	v_add_f32_e32 v130, 0x3727c5ac, v130
	v_mul_f32_e32 v132, 0x4b800000, v130
	v_cmp_gt_f32_e32 vcc, s56, v130
	s_nop 1
	v_cndmask_b32_e32 v130, v130, v132, vcc
	v_rsq_f32_e32 v130, v130
	s_nop 0
	v_mul_f32_e32 v132, 0x45800000, v130
	v_cndmask_b32_e32 v133, v130, v132, vcc
	v_mov_b32_e32 v132, v131
	ds_write_b64 v206, v[132:133] offset:8192

; DI void ln_exchange(const AccT& acc, LAS float* red, float* stats, unsigned* cnt, int pm, int pn, int tid, int wr, int wc, int fr, int fq) {
;     ...
;   if (tid < 256) { float a = 0.f, b = 0.f;
; #pragma unroll
;     for (int w = 0; w < 4; ++w) { a += red[(tid * 4 + w) * 2]; b += red[(tid * 4 + w) * 2 + 1]; }
;     float* sp = stats + ((size_t)(pm * 256 + tid) * 8 + pn) * 2;
;     __hip_atomic_store(sp, a, __ATOMIC_RELAXED, __HIP_MEMORY_SCOPE_AGENT); __hip_atomic_store(sp + 1, b, __ATOMIC_RELAXED, __HIP_MEMORY_SCOPE_AGENT); }
;   asm volatile("s_waitcnt vmcnt(0)" ::: "memory");
;   __syncthreads();
;   if (tid == 0) {
;     __builtin_amdgcn_fence(__ATOMIC_RELEASE, "agent");
;     asm volatile("s_waitcnt vmcnt(0)" ::: "memory");
;     __hip_atomic_fetch_add(cnt + pm, 1u, __ATOMIC_RELAXED, __HIP_MEMORY_SCOPE_AGENT);
;   DI void fused(AccT& acc, const Unit& u, LAS unsigned char* lds, int tid, int wr, int wc, int fr, int fq) const {
;     ...
;       ln_exchange(acc, red, stats + (size_t)32 * 256 * 16, cnt + 32, u.pm, u.pn, tid, wr, wc, fr, fq);
.LBB0_1838:
	s_or_b64 exec, exec, s[14:15]
	s_waitcnt lgkmcnt(0)
	s_barrier
	s_and_saveexec_b64 s[0:1], s[2:3]
	s_cbranch_execz .LBB0_1840
	ds_read_b128 v[70:73], v209
	ds_read_b128 v[74:77], v209 offset:16
	v_readlane_b32 s14, v251, 32
	v_readlane_b32 s15, v251, 33
	s_ashr_i32 s11, s10, 31
	s_waitcnt lgkmcnt(1)
	v_add_f32_e32 v4, 0, v71
	v_add_f32_e32 v4, v4, v73
	v_add_f32_e32 v0, 0, v70
	s_waitcnt lgkmcnt(0)
	v_add_f32_e32 v4, v4, v75
	v_add_f32_e32 v0, v0, v72
	v_add_f32_e32 v70, v4, v77
	v_lshlrev_b64 v[4:5], 6, v[182:183]
	v_add_f32_e32 v0, v0, v74
	v_lshl_add_u64 v[4:5], s[14:15], 0, v[4:5]
	v_add_f32_e32 v0, v0, v76
	v_lshl_add_u64 v[4:5], s[10:11], 3, v[4:5]
	v_mov_b32_e32 v71, v70
	v_mov_b32_e32 v70, v0
	s_nop 0
	global_store_dwordx2 v[4:5], v[70:71], off sc1
.LBB0_1840:
	s_or_b64 exec, exec, s[0:1]
	s_waitcnt vmcnt(0)
	s_barrier
	s_and_saveexec_b64 s[0:1], s[4:5]
	s_cbranch_execz .LBB0_1857
	s_ashr_i32 s9, s8, 31
	s_lshl_b64 s[4:5], s[8:9], 2
	s_mov_b64 s[8:9], exec
	s_waitcnt vmcnt(0)
	s_waitcnt vmcnt(0)
	v_mbcnt_lo_u32_b32 v0, s8, 0
	s_add_u32 s4, s24, s4
	v_mbcnt_hi_u32_b32 v0, s9, v0
	s_addc_u32 s5, s25, s5
	v_cmp_eq_u32_e32 vcc, 0, v0
	s_and_saveexec_b64 s[10:11], vcc
	s_cbranch_execz .LBB0_1843
	s_bcnt1_i32_b64 s8, s[8:9]
	v_mov_b32_e32 v0, s8
	global_atomic_add v1, v0, s[4:5] offset:128

; DI void ln_exchange(const AccT& acc, LAS float* red, float* stats, unsigned* cnt, int pm, int pn, int tid, int wr, int wc, int fr, int fq) {
;     ...
;     while (__hip_atomic_load(cnt + pm, __ATOMIC_RELAXED, __HIP_MEMORY_SCOPE_AGENT) < 8u) { __builtin_amdgcn_s_sleep(1); if (++sp_ > (1u << 24)) break; }
;     __builtin_amdgcn_fence(__ATOMIC_ACQUIRE, "agent");
;     asm volatile("s_waitcnt vmcnt(0)" ::: "memory");
;   }
;   __syncthreads();
;   if (tid < 256) { float a = 0.f, b = 0.f; const float* sp = stats + (size_t)(pm * 256 + tid) * 16;
; #pragma unroll
;     for (int w = 0; w < 8; ++w) { a += __hip_atomic_load(sp + 2 * w, __ATOMIC_RELAXED, __HIP_MEMORY_SCOPE_AGENT); b += __hip_atomic_load(sp + 2 * w + 1, __ATOMIC_RELAXED, __HIP_MEMORY_SCOPE_AGENT); }
;     const float mean = a * (1.f / DM), var = fmaxf(b * (1.f / DM) - mean * mean, 0.f);
;     red[2048 + tid * 2] = mean; red[2048 + tid * 2 + 1] = rsqrtf(var + 1e-5f); }
.LBB0_1846:
	global_load_dword v0, v1, s[4:5] offset:128 sc1
	s_mov_b64 s[8:9], -1
	s_waitcnt vmcnt(0)
	v_cmp_lt_u32_e32 vcc, 7, v0
	s_cbranch_vccnz .LBB0_1845
	s_cmp_lg_u32 s10, 0
	s_sleep 1
	s_cbranch_scc0 .LBB0_1844
	global_load_dword v0, v1, s[4:5] offset:128 sc1
	s_waitcnt vmcnt(0)
	v_cmp_gt_u32_e32 vcc, 8, v0
	s_cbranch_vccz .LBB0_1845
	s_sleep 1
	global_load_dword v0, v1, s[4:5] offset:128 sc1
	s_waitcnt vmcnt(0)
	v_cmp_gt_u32_e32 vcc, 8, v0
	s_cbranch_vccz .LBB0_1845
	s_sleep 1
	global_load_dword v0, v1, s[4:5] offset:128 sc1
	s_waitcnt vmcnt(0)
	v_cmp_gt_u32_e32 vcc, 8, v0
	s_cbranch_vccz .LBB0_1845
	s_sleep 1
	global_load_dword v0, v1, s[4:5] offset:128 sc1
	s_waitcnt vmcnt(0)
	v_cmp_gt_u32_e32 vcc, 8, v0
	s_cbranch_vccz .LBB0_1845
	s_sleep 1
	global_load_dword v0, v1, s[4:5] offset:128 sc1
	s_waitcnt vmcnt(0)
	v_cmp_gt_u32_e32 vcc, 8, v0
	s_cbranch_vccz .LBB0_1845
	s_sleep 1
	global_load_dword v0, v1, s[4:5] offset:128 sc1
	s_waitcnt vmcnt(0)
	v_cmp_gt_u32_e32 vcc, 8, v0
	s_cbranch_vccz .LBB0_1845
	s_sleep 1
	global_load_dword v0, v1, s[4:5] offset:128 sc1
	s_waitcnt vmcnt(0)
	v_cmp_gt_u32_e32 vcc, 8, v0
	s_cbranch_vccz .LBB0_1845
	s_sleep 1
	s_add_i32 s10, s10, -8
	s_mov_b64 s[8:9], 0
	s_branch .LBB0_1845
.LBB0_1856:
	s_waitcnt vmcnt(0)
.LBB0_1857:
	s_or_b64 exec, exec, s[0:1]
	s_barrier
	s_and_saveexec_b64 s[0:1], s[2:3]
	s_cbranch_execz .LBB0_1859
	v_readlane_b32 s2, v251, 32
	v_lshlrev_b64 v[4:5], 6, v[182:183]
	v_readlane_b32 s3, v251, 33
	s_nop 1
	v_lshl_add_u64 v[4:5], s[2:3], 0, v[4:5]
	global_load_dwordx4 v[70:73], v[4:5], off sc1
	global_load_dwordx4 v[74:77], v[4:5], off offset:16 sc1
	global_load_dwordx4 v[78:81], v[4:5], off offset:32 sc1
	global_load_dwordx4 v[82:85], v[4:5], off offset:48 sc1
	s_mov_b32 s2, 0x3a000000
	s_waitcnt vmcnt(3)
	v_pk_add_f32 v[4:5], v[70:71], 0 op_sel:[1,0] op_sel_hi:[0,0]
	v_pk_add_f32 v[4:5], v[4:5], v[72:73] op_sel:[0,1] op_sel_hi:[1,0]
	s_waitcnt vmcnt(2)
	v_pk_add_f32 v[4:5], v[4:5], v[74:75] op_sel:[0,1] op_sel_hi:[1,0]
	v_pk_add_f32 v[4:5], v[4:5], v[76:77] op_sel:[0,1] op_sel_hi:[1,0]
	s_waitcnt vmcnt(1)
	v_pk_add_f32 v[4:5], v[4:5], v[78:79] op_sel:[0,1] op_sel_hi:[1,0]
	v_pk_add_f32 v[4:5], v[4:5], v[80:81] op_sel:[0,1] op_sel_hi:[1,0]
	s_waitcnt vmcnt(0)
	v_pk_add_f32 v[4:5], v[4:5], v[82:83] op_sel:[0,1] op_sel_hi:[1,0]
	v_pk_add_f32 v[4:5], v[4:5], v[84:85] op_sel:[0,1] op_sel_hi:[1,0]
	s_nop 0
	v_pk_mul_f32 v[4:5], v[4:5], s[2:3] op_sel_hi:[1,0]
	s_nop 0
	v_fma_f32 v0, -v5, v5, v4
	v_max_f32_e32 v0, 0, v0
	v_add_f32_e32 v0, 0x3727c5ac, v0
	v_mul_f32_e32 v4, 0x4b800000, v0
	v_cmp_gt_f32_e32 vcc, s56, v0
	v_mov_b32_e32 v70, v5
	s_nop 0
	v_cndmask_b32_e32 v0, v0, v4, vcc
	v_rsq_f32_e32 v0, v0
	s_nop 0
	v_mul_f32_e32 v4, 0x45800000, v0
	v_cndmask_b32_e32 v71, v0, v4, vcc
	ds_write_b64 v206, v[70:71] offset:8192

; DI void ln_exchange(const AccT& acc, LAS float* red, float* stats, unsigned* cnt, int pm, int pn, int tid, int wr, int wc, int fr, int fq) {
;     ...
;   if (tid < 256) { float a = 0.f, b = 0.f;
; #pragma unroll
;     for (int w = 0; w < 4; ++w) { a += red[(tid * 4 + w) * 2]; b += red[(tid * 4 + w) * 2 + 1]; }
;     float* sp = stats + ((size_t)(pm * 256 + tid) * 8 + pn) * 2;
;     __hip_atomic_store(sp, a, __ATOMIC_RELAXED, __HIP_MEMORY_SCOPE_AGENT); __hip_atomic_store(sp + 1, b, __ATOMIC_RELAXED, __HIP_MEMORY_SCOPE_AGENT); }
;   asm volatile("s_waitcnt vmcnt(0)" ::: "memory");
;   __syncthreads();
;   if (tid == 0) {
;     __builtin_amdgcn_fence(__ATOMIC_RELEASE, "agent");
;     asm volatile("s_waitcnt vmcnt(0)" ::: "memory");
;     __hip_atomic_fetch_add(cnt + pm, 1u, __ATOMIC_RELAXED, __HIP_MEMORY_SCOPE_AGENT);
.LBB0_2014:
	s_or_b64 exec, exec, s[2:3]
	s_movk_i32 s2, 0x100
	v_add_u32_e32 v202, s23, v220
	v_cmp_gt_i32_e64 s[2:3], s2, v220
	v_ashrrev_i32_e32 v203, 31, v202
	s_waitcnt lgkmcnt(0)
	s_barrier
	s_and_saveexec_b64 s[4:5], s[2:3]
	s_cbranch_execz .LBB0_2016
	v_lshl_add_u32 v134, v220, 5, 0
	ds_read_b128 v[130:133], v134
	ds_read_b128 v[134:137], v134 offset:16
	v_readlane_b32 s14, v251, 28
	v_readlane_b32 s15, v251, 29
	s_ashr_i32 s11, s10, 31
	s_waitcnt lgkmcnt(1)
	v_add_f32_e32 v130, 0, v130
	v_add_f32_e32 v131, 0, v131
	v_add_f32_e32 v130, v130, v132
	v_add_f32_e32 v131, v131, v133
	s_waitcnt lgkmcnt(0)
	v_add_f32_e32 v130, v130, v134
	v_add_f32_e32 v131, v131, v135
	v_add_f32_e32 v132, v130, v136
	v_add_f32_e32 v133, v131, v137
	v_lshlrev_b64 v[130:131], 6, v[202:203]
	v_lshl_add_u64 v[130:131], s[14:15], 0, v[130:131]
	v_lshl_add_u64 v[130:131], s[10:11], 3, v[130:131]
	global_store_dwordx2 v[130:131], v[132:133], off sc1
.LBB0_2016:
	s_or_b64 exec, exec, s[4:5]
	s_lshl_b32 s72, s6, 6
	s_lshl_b64 s[4:5], s[72:73], 2
	v_readlane_b32 s9, v251, 30
	s_waitcnt vmcnt(0)
	s_add_u32 s25, s9, s4
	v_readlane_b32 s4, v251, 31
	s_addc_u32 s26, s4, s5
	v_cmp_eq_u32_e64 s[4:5], 0, v220
	s_barrier
	s_and_saveexec_b64 s[14:15], s[4:5]
	s_cbranch_execz .LBB0_2033
	s_mov_b64 s[18:19], exec
	s_ashr_i32 s9, s8, 31
	s_waitcnt vmcnt(0)
	s_waitcnt vmcnt(0)
	s_lshl_b64 s[16:17], s[8:9], 2
	v_mbcnt_lo_u32_b32 v130, s18, 0
	s_add_u32 s16, s25, s16
	v_mbcnt_hi_u32_b32 v130, s19, v130
	s_addc_u32 s17, s26, s17
	v_cmp_eq_u32_e32 vcc, 0, v130
	s_and_saveexec_b64 s[20:21], vcc
	s_cbranch_execz .LBB0_2019
	s_bcnt1_i32_b64 s9, s[18:19]
	v_mov_b32_e32 v130, s9
	global_atomic_add v1, v130, s[16:17]

; DI void ln_exchange(const AccT& acc, LAS float* red, float* stats, unsigned* cnt, int pm, int pn, int tid, int wr, int wc, int fr, int fq) {
;     ...
;     while (__hip_atomic_load(cnt + pm, __ATOMIC_RELAXED, __HIP_MEMORY_SCOPE_AGENT) < 8u) { __builtin_amdgcn_s_sleep(1); if (++sp_ > (1u << 24)) break; }
;     __builtin_amdgcn_fence(__ATOMIC_ACQUIRE, "agent");
;     asm volatile("s_waitcnt vmcnt(0)" ::: "memory");
;   }
;   __syncthreads();
;   if (tid < 256) { float a = 0.f, b = 0.f; const float* sp = stats + (size_t)(pm * 256 + tid) * 16;
; #pragma unroll
;     for (int w = 0; w < 8; ++w) { a += __hip_atomic_load(sp + 2 * w, __ATOMIC_RELAXED, __HIP_MEMORY_SCOPE_AGENT); b += __hip_atomic_load(sp + 2 * w + 1, __ATOMIC_RELAXED, __HIP_MEMORY_SCOPE_AGENT); }
;     const float mean = a * (1.f / DM), var = fmaxf(b * (1.f / DM) - mean * mean, 0.f);
;     red[2048 + tid * 2] = mean; red[2048 + tid * 2 + 1] = rsqrtf(var + 1e-5f); }
.LBB0_2022:
	global_load_dword v130, v1, s[16:17] sc1
	s_mov_b64 s[18:19], -1
	s_waitcnt vmcnt(0)
	v_cmp_lt_u32_e32 vcc, 7, v130
	s_cbranch_vccnz .LBB0_2021
	s_cmp_lg_u32 s9, 0
	s_sleep 1
	s_cbranch_scc0 .LBB0_2020
	global_load_dword v130, v1, s[16:17] sc1
	s_waitcnt vmcnt(0)
	v_cmp_gt_u32_e32 vcc, 8, v130
	s_cbranch_vccz .LBB0_2021
	s_sleep 1
	global_load_dword v130, v1, s[16:17] sc1
	s_waitcnt vmcnt(0)
	v_cmp_gt_u32_e32 vcc, 8, v130
	s_cbranch_vccz .LBB0_2021
	s_sleep 1
	global_load_dword v130, v1, s[16:17] sc1
	s_waitcnt vmcnt(0)
	v_cmp_gt_u32_e32 vcc, 8, v130
	s_cbranch_vccz .LBB0_2021
	s_sleep 1
	global_load_dword v130, v1, s[16:17] sc1
	s_waitcnt vmcnt(0)
	v_cmp_gt_u32_e32 vcc, 8, v130
	s_cbranch_vccz .LBB0_2021
	s_sleep 1
	global_load_dword v130, v1, s[16:17] sc1
	s_waitcnt vmcnt(0)
	v_cmp_gt_u32_e32 vcc, 8, v130
	s_cbranch_vccz .LBB0_2021
	s_sleep 1
	global_load_dword v130, v1, s[16:17] sc1
	s_waitcnt vmcnt(0)
	v_cmp_gt_u32_e32 vcc, 8, v130
	s_cbranch_vccz .LBB0_2021
	s_sleep 1
	global_load_dword v130, v1, s[16:17] sc1
	s_waitcnt vmcnt(0)
	v_cmp_gt_u32_e32 vcc, 8, v130
	s_cbranch_vccz .LBB0_2021
	s_sleep 1
	s_add_i32 s9, s9, -8
	s_mov_b64 s[18:19], 0
	s_branch .LBB0_2021
.LBB0_2032:
	s_waitcnt vmcnt(0)
.LBB0_2033:
	s_or_b64 exec, exec, s[14:15]
	s_barrier
	s_and_saveexec_b64 s[14:15], s[2:3]
	s_cbranch_execz .LBB0_2035
	v_readlane_b32 s16, v251, 28
	v_lshlrev_b64 v[130:131], 6, v[202:203]
	v_readlane_b32 s17, v251, 29
	s_nop 1
	v_lshl_add_u64 v[130:131], s[16:17], 0, v[130:131]
	global_load_dwordx4 v[132:135], v[130:131], off sc1
	global_load_dwordx4 v[136:139], v[130:131], off offset:16 sc1
	global_load_dwordx4 v[140:143], v[130:131], off offset:32 sc1
	global_load_dwordx4 v[144:147], v[130:131], off offset:48 sc1
	s_mov_b32 s16, 0x3a000000
	s_waitcnt vmcnt(3)
	v_pk_add_f32 v[130:131], v[132:133], 0 op_sel:[1,0] op_sel_hi:[0,0]
	v_pk_add_f32 v[130:131], v[130:131], v[134:135] op_sel:[0,1] op_sel_hi:[1,0]
	v_lshl_add_u32 v134, v220, 3, 0
	s_waitcnt vmcnt(2)
	v_pk_add_f32 v[130:131], v[130:131], v[136:137] op_sel:[0,1] op_sel_hi:[1,0]
	v_pk_add_f32 v[130:131], v[130:131], v[138:139] op_sel:[0,1] op_sel_hi:[1,0]
	s_waitcnt vmcnt(1)
	v_pk_add_f32 v[130:131], v[130:131], v[140:141] op_sel:[0,1] op_sel_hi:[1,0]
	v_pk_add_f32 v[130:131], v[130:131], v[142:143] op_sel:[0,1] op_sel_hi:[1,0]
	s_waitcnt vmcnt(0)
	v_pk_add_f32 v[130:131], v[130:131], v[144:145] op_sel:[0,1] op_sel_hi:[1,0]
	v_pk_add_f32 v[130:131], v[130:131], v[146:147] op_sel:[0,1] op_sel_hi:[1,0]
	s_nop 0
	v_pk_mul_f32 v[130:131], v[130:131], s[16:17] op_sel_hi:[1,0]
	s_nop 0
	v_fma_f32 v130, -v131, v131, v130
	v_max_f32_e32 v130, 0, v130
	v_add_f32_e32 v130, 0x3727c5ac, v130
	v_mul_f32_e32 v132, 0x4b800000, v130
	v_cmp_gt_f32_e32 vcc, s27, v130
	s_nop 1
	v_cndmask_b32_e32 v130, v130, v132, vcc
	v_rsq_f32_e32 v130, v130
	s_nop 0
	v_mul_f32_e32 v132, 0x45800000, v130
	v_cndmask_b32_e32 v133, v130, v132, vcc
	v_mov_b32_e32 v132, v131
	ds_write_b64 v134, v[132:133] offset:8192

; DI void ln_exchange(const AccT& acc, LAS float* red, float* stats, unsigned* cnt, int pm, int pn, int tid, int wr, int wc, int fr, int fq) {
;     ...
;   if (tid < 256) { float a = 0.f, b = 0.f;
; #pragma unroll
;     for (int w = 0; w < 4; ++w) { a += red[(tid * 4 + w) * 2]; b += red[(tid * 4 + w) * 2 + 1]; }
;     float* sp = stats + ((size_t)(pm * 256 + tid) * 8 + pn) * 2;
;     __hip_atomic_store(sp, a, __ATOMIC_RELAXED, __HIP_MEMORY_SCOPE_AGENT); __hip_atomic_store(sp + 1, b, __ATOMIC_RELAXED, __HIP_MEMORY_SCOPE_AGENT); }
;   asm volatile("s_waitcnt vmcnt(0)" ::: "memory");
;   __syncthreads();
;   if (tid == 0) {
;     __builtin_amdgcn_fence(__ATOMIC_RELEASE, "agent");
;     asm volatile("s_waitcnt vmcnt(0)" ::: "memory");
;     __hip_atomic_fetch_add(cnt + pm, 1u, __ATOMIC_RELAXED, __HIP_MEMORY_SCOPE_AGENT);
;   DI void fused(AccT& acc, const Unit& u, LAS unsigned char* lds, int tid, int wr, int wc, int fr, int fq) const {
;     ...
;       ln_exchange(acc, red, stats + (size_t)32 * 256 * 16, cnt + 32, u.pm, u.pn, tid, wr, wc, fr, fq);
.LBB0_2052:
	s_or_b64 exec, exec, s[6:7]
	s_waitcnt lgkmcnt(0)
	s_barrier
	s_and_saveexec_b64 s[0:1], s[2:3]
	s_cbranch_execz .LBB0_2054
	v_lshl_add_u32 v0, v220, 5, 0
	ds_read_b128 v[66:69], v0
	ds_read_b128 v[70:73], v0 offset:16
	v_readlane_b32 s6, v251, 32
	v_readlane_b32 s7, v251, 33
	s_ashr_i32 s11, s10, 31
	s_waitcnt lgkmcnt(1)
	v_add_f32_e32 v0, 0, v66
	v_add_f32_e32 v66, 0, v67
	v_add_f32_e32 v66, v66, v69
	s_waitcnt lgkmcnt(0)
	v_add_f32_e32 v66, v66, v71
	v_add_f32_e32 v0, v0, v68
	v_add_f32_e32 v68, v66, v73
	v_lshlrev_b64 v[66:67], 6, v[202:203]
	v_add_f32_e32 v0, v0, v70
	v_lshl_add_u64 v[66:67], s[6:7], 0, v[66:67]
	v_add_f32_e32 v0, v0, v72
	v_lshl_add_u64 v[66:67], s[10:11], 3, v[66:67]
	v_mov_b32_e32 v69, v68
	v_mov_b32_e32 v68, v0
	s_nop 0
	global_store_dwordx2 v[66:67], v[68:69], off sc1
.LBB0_2054:
	s_or_b64 exec, exec, s[0:1]
	s_waitcnt vmcnt(0)
	s_barrier
	s_and_saveexec_b64 s[0:1], s[4:5]
	s_cbranch_execz .LBB0_2071
	s_ashr_i32 s9, s8, 31
	s_mov_b64 s[6:7], exec
	s_waitcnt vmcnt(0)
	s_waitcnt vmcnt(0)
	s_lshl_b64 s[4:5], s[8:9], 2
	v_mbcnt_lo_u32_b32 v0, s6, 0
	s_add_u32 s4, s25, s4
	v_mbcnt_hi_u32_b32 v0, s7, v0
	s_addc_u32 s5, s26, s5
	v_cmp_eq_u32_e32 vcc, 0, v0
	s_and_saveexec_b64 s[8:9], vcc
	s_cbranch_execz .LBB0_2057
	s_bcnt1_i32_b64 s6, s[6:7]
	v_mov_b32_e32 v0, s6
	global_atomic_add v1, v0, s[4:5] offset:128

; DI void ln_exchange(const AccT& acc, LAS float* red, float* stats, unsigned* cnt, int pm, int pn, int tid, int wr, int wc, int fr, int fq) {
;     ...
;     while (__hip_atomic_load(cnt + pm, __ATOMIC_RELAXED, __HIP_MEMORY_SCOPE_AGENT) < 8u) { __builtin_amdgcn_s_sleep(1); if (++sp_ > (1u << 24)) break; }
;     __builtin_amdgcn_fence(__ATOMIC_ACQUIRE, "agent");
;     asm volatile("s_waitcnt vmcnt(0)" ::: "memory");
;   }
;   __syncthreads();
;   if (tid < 256) { float a = 0.f, b = 0.f; const float* sp = stats + (size_t)(pm * 256 + tid) * 16;
; #pragma unroll
;     for (int w = 0; w < 8; ++w) { a += __hip_atomic_load(sp + 2 * w, __ATOMIC_RELAXED, __HIP_MEMORY_SCOPE_AGENT); b += __hip_atomic_load(sp + 2 * w + 1, __ATOMIC_RELAXED, __HIP_MEMORY_SCOPE_AGENT); }
;     const float mean = a * (1.f / DM), var = fmaxf(b * (1.f / DM) - mean * mean, 0.f);
;     red[2048 + tid * 2] = mean; red[2048 + tid * 2 + 1] = rsqrtf(var + 1e-5f); }
.LBB0_2060:
	global_load_dword v0, v1, s[4:5] offset:128 sc1
	s_mov_b64 s[6:7], -1
	s_waitcnt vmcnt(0)
	v_cmp_lt_u32_e32 vcc, 7, v0
	s_cbranch_vccnz .LBB0_2059
	s_cmp_lg_u32 s8, 0
	s_sleep 1
	s_cbranch_scc0 .LBB0_2058
	global_load_dword v0, v1, s[4:5] offset:128 sc1
	s_waitcnt vmcnt(0)
	v_cmp_gt_u32_e32 vcc, 8, v0
	s_cbranch_vccz .LBB0_2059
	s_sleep 1
	global_load_dword v0, v1, s[4:5] offset:128 sc1
	s_waitcnt vmcnt(0)
	v_cmp_gt_u32_e32 vcc, 8, v0
	s_cbranch_vccz .LBB0_2059
	s_sleep 1
	global_load_dword v0, v1, s[4:5] offset:128 sc1
	s_waitcnt vmcnt(0)
	v_cmp_gt_u32_e32 vcc, 8, v0
	s_cbranch_vccz .LBB0_2059
	s_sleep 1
	global_load_dword v0, v1, s[4:5] offset:128 sc1
	s_waitcnt vmcnt(0)
	v_cmp_gt_u32_e32 vcc, 8, v0
	s_cbranch_vccz .LBB0_2059
	s_sleep 1
	global_load_dword v0, v1, s[4:5] offset:128 sc1
	s_waitcnt vmcnt(0)
	v_cmp_gt_u32_e32 vcc, 8, v0
	s_cbranch_vccz .LBB0_2059
	s_sleep 1
	global_load_dword v0, v1, s[4:5] offset:128 sc1
	s_waitcnt vmcnt(0)
	v_cmp_gt_u32_e32 vcc, 8, v0
	s_cbranch_vccz .LBB0_2059
	s_sleep 1
	global_load_dword v0, v1, s[4:5] offset:128 sc1
	s_waitcnt vmcnt(0)
	v_cmp_gt_u32_e32 vcc, 8, v0
	s_cbranch_vccz .LBB0_2059
	s_sleep 1
	s_add_i32 s8, s8, -8
	s_mov_b64 s[6:7], 0
	s_branch .LBB0_2059
.LBB0_2070:
	s_waitcnt vmcnt(0)
.LBB0_2071:
	s_or_b64 exec, exec, s[0:1]
	s_barrier
	s_and_saveexec_b64 s[0:1], s[2:3]
	s_cbranch_execz .LBB0_2073
	v_readlane_b32 s2, v251, 32
	v_lshlrev_b64 v[66:67], 6, v[202:203]
	v_readlane_b32 s3, v251, 33
	s_nop 1
	v_lshl_add_u64 v[66:67], s[2:3], 0, v[66:67]
	global_load_dwordx4 v[68:71], v[66:67], off sc1
	global_load_dwordx4 v[72:75], v[66:67], off offset:16 sc1
	global_load_dwordx4 v[76:79], v[66:67], off offset:32 sc1
	global_load_dwordx2 v[80:81], v[66:67], off offset:48 sc1
	global_load_dwordx2 v[84:85], v[66:67], off offset:56 sc1
	s_mov_b32 s2, 0x3a000000
	s_waitcnt vmcnt(4)
	v_pk_add_f32 v[66:67], v[68:69], 0 op_sel:[1,0] op_sel_hi:[0,0]
	v_pk_add_f32 v[66:67], v[66:67], v[70:71] op_sel:[0,1] op_sel_hi:[1,0]
	s_waitcnt vmcnt(3)
	v_pk_add_f32 v[66:67], v[66:67], v[72:73] op_sel:[0,1] op_sel_hi:[1,0]
	v_pk_add_f32 v[66:67], v[66:67], v[74:75] op_sel:[0,1] op_sel_hi:[1,0]
	s_waitcnt vmcnt(2)
	v_pk_add_f32 v[66:67], v[66:67], v[76:77] op_sel:[0,1] op_sel_hi:[1,0]
	v_pk_add_f32 v[66:67], v[66:67], v[78:79] op_sel:[0,1] op_sel_hi:[1,0]
	s_waitcnt vmcnt(1)
	v_pk_add_f32 v[66:67], v[66:67], v[80:81] op_sel:[0,1] op_sel_hi:[1,0]
	s_waitcnt vmcnt(0)
	v_pk_add_f32 v[66:67], v[66:67], v[84:85] op_sel:[0,1] op_sel_hi:[1,0]
	s_nop 0
	v_pk_mul_f32 v[66:67], v[66:67], s[2:3] op_sel_hi:[1,0]
	s_nop 0
	v_fma_f32 v0, -v67, v67, v66
	v_max_f32_e32 v0, 0, v0
	v_add_f32_e32 v0, 0x3727c5ac, v0
	v_mul_f32_e32 v66, 0x4b800000, v0
	v_cmp_gt_f32_e32 vcc, s27, v0
	s_nop 1
	v_cndmask_b32_e32 v0, v0, v66, vcc
	v_rsq_f32_e32 v0, v0
	v_lshl_add_u32 v66, v220, 3, 0
	v_mul_f32_e32 v68, 0x45800000, v0
	v_cndmask_b32_e32 v69, v0, v68, vcc
	v_mov_b32_e32 v68, v67
	ds_write_b64 v66, v[68:69] offset:8192
